# v40: v37 + static s_setprio 1 for waves 4-7 during the prompt attention item loops (P3, P4)
# baseline (speedup 1.0000x reference)
; DI int crow(int reg, int h) { return (reg & 3) + 8 * (reg >> 2) + 4 * h; }
;     DI void init_s(f32x16& s, int) const { zero16(s); }
;     DI void init_s(f32x16& s, int) const { zero16(s); }
;     DI void init_s(f32x16& s, int) const { zero16(s); }
;     DI void init_s(f32x16& s, int tl) const { const int h = (threadIdx.x & 63) >> 5; const float c0 = slope2 * (float)(32 * tl) - lc;
; #pragma unroll
;         for (int i = 0; i < 16; ++i) s[i] = slope2 * (float)crow(i, h) + c0; }
;     DI void post_s(f32x16& s, int tl, int r, int h) const {
;         if (tl == g - 4) {
; #pragma unroll
;             for (int i = 0; i < 16; ++i) s[i] = crow(i, h) > r ? s[i] : -INFINITY; }
;         if (tl == g) {
; #pragma unroll
;             for (int i = 0; i < 16; ++i) s[i] = crow(i, h) <= r ? s[i] : -INFINITY; } }
.LBB0_954:
	s_waitcnt vmcnt(0)
	s_barrier
	s_mov_b64 s[4:5], exec
	v_readlane_b32 s6, v242, 0
	v_readlane_b32 s7, v242, 1
	s_and_b64 s[6:7], s[4:5], s[6:7]
	s_mov_b64 exec, s[6:7]
	s_add_i32 s6, 0, 0x20210
	v_mov_b32_e32 v1, 0
	v_mov_b32_e32 v2, s6
	ds_write_b32 v2, v1
	s_or_b64 exec, exec, s[4:5]
	v_and_b32_e32 v6, 1, v171
	v_and_b32_e32 v1, 31, v183
	v_lshlrev_b32_e32 v2, 9, v6
	v_mov_b32_e32 v3, 0
	v_lshl_add_u64 v[4:5], s[68:69], 0, v[2:3]
	v_lshlrev_b32_e32 v8, 4, v1
	v_mov_b32_e32 v9, v3
	v_lshlrev_b32_e32 v186, 2, v6
	v_lshl_add_u64 v[188:189], v[4:5], 0, v[8:9]
	v_cvt_f32_ubyte0_e32 v4, s33
	v_lshlrev_b32_e32 v184, 3, v6
	v_or_b32_e32 v6, 2, v186
	v_rcp_iflag_f32_e32 v4, v4
	v_cmp_gt_u32_e64 s[10:11], v6, v1
	v_or_b32_e32 v6, 3, v186
	v_cmp_gt_u32_e64 s[12:13], v6, v1
	v_or_b32_e32 v6, 8, v186
	v_cmp_gt_u32_e64 s[14:15], v6, v1
	v_or_b32_e32 v6, 9, v186
	v_cmp_gt_u32_e64 s[16:17], v6, v1
	v_or_b32_e32 v6, 10, v186
	v_mul_f32_e32 v4, 0x4f7ffffe, v4
	v_cmp_gt_u32_e64 s[18:19], v6, v1
	v_or_b32_e32 v6, 11, v186
	v_cvt_u32_f32_e32 v4, v4
	v_cmp_gt_u32_e64 s[20:21], v6, v1
	v_or_b32_e32 v6, 16, v186
	v_cmp_gt_u32_e64 s[22:23], v6, v1
	v_or_b32_e32 v6, 17, v186
	v_cmp_gt_u32_e64 s[24:25], v6, v1
	v_or_b32_e32 v6, 18, v186
	v_cmp_gt_u32_e64 s[26:27], v6, v1
	v_or_b32_e32 v6, 19, v186
	s_sub_i32 s40, 0, s33
	v_readfirstlane_b32 s41, v4
	v_cmp_gt_u32_e64 s[28:29], v6, v1
	v_or_b32_e32 v6, 24, v186
	s_mul_i32 s40, s40, s41
	v_cmp_gt_u32_e64 s[30:31], v6, v1
	v_or_b32_e32 v6, 25, v186
	s_mul_hi_u32 s40, s41, s40
	v_cmp_gt_u32_e64 s[34:35], v6, v1
	v_or_b32_e32 v6, 26, v186
	s_add_i32 s51, s41, s40
	v_lshlrev_b32_e32 v4, 5, v183
	s_movk_i32 s40, 0x400
	v_cmp_gt_u32_e64 s[36:37], v6, v1
	v_or_b32_e32 v6, 27, v186
	v_and_or_b32 v4, v4, s40, v8
	v_mov_b32_e32 v5, v3
	v_cmp_gt_u32_e64 s[38:39], v6, v1
	v_lshl_add_u64 v[6:7], s[66:67], 0, v[2:3]
	v_lshl_add_u64 v[4:5], s[42:43], 0, v[4:5]
	s_mov_b64 s[40:41], 0x6e00800
	v_or_b32_e32 v2, v2, v8
	v_lshl_add_u64 v[208:209], v[4:5], 0, s[40:41]
	v_lshl_add_u64 v[210:211], s[42:43], 0, v[2:3]
	s_mov_b64 s[40:41], 0x7602800
	v_lshl_add_u64 v[212:213], v[210:211], 0, s[40:41]
	v_lshlrev_b32_e32 v2, 6, v183
	s_movk_i32 s40, 0x800
	v_and_b32_e32 v10, 4, v170
	v_and_or_b32 v2, v2, s40, v8
	v_or_b32_e32 v11, 1, v10
	v_or_b32_e32 v12, 3, v10
	v_or_b32_e32 v13, 2, v10
	v_or_b32_e32 v14, 9, v10
	v_or_b32_e32 v15, 8, v10
	v_or_b32_e32 v16, 11, v10
	v_or_b32_e32 v17, 10, v10
	v_or_b32_e32 v18, 17, v10
	v_or_b32_e32 v19, 16, v10
	v_or_b32_e32 v20, 19, v10
	v_or_b32_e32 v21, 18, v10
	v_or_b32_e32 v22, 25, v10
	v_or_b32_e32 v23, 24, v10
	v_or_b32_e32 v24, 27, v10
	v_or_b32_e32 v25, 26, v10
	v_lshl_add_u64 v[214:215], s[42:43], 0, v[2:3]
	v_mbcnt_lo_u32_b32 v2, -1, 0
	s_mov_b32 s73, 0
	v_cmp_eq_u32_e64 s[4:5], 0, v182
	s_add_i32 s47, s2, -16
	s_add_i32 s50, s2, 0xf00
	v_cmp_gt_u32_e64 s[6:7], v186, v1
	v_cmp_lt_u32_e64 s[8:9], v186, v1
	v_cvt_f32_ubyte0_e32 v191, v24
	v_cvt_f32_ubyte0_e32 v190, v25
	v_cvt_f32_ubyte0_e32 v193, v22
	v_cvt_f32_ubyte0_e32 v192, v23
	v_cvt_f32_ubyte0_e32 v195, v20
	v_cvt_f32_ubyte0_e32 v194, v21
	v_cvt_f32_ubyte0_e32 v197, v18
	v_cvt_f32_ubyte0_e32 v196, v19
	v_cvt_f32_ubyte0_e32 v199, v16
	v_cvt_f32_ubyte0_e32 v198, v17
	v_cvt_f32_ubyte0_e32 v201, v14
	v_cvt_f32_ubyte0_e32 v200, v15
	v_cvt_f32_ubyte0_e32 v203, v12
	v_cvt_f32_ubyte0_e32 v202, v13
	v_cvt_f32_ubyte0_e32 v204, v10
	v_cvt_f32_ubyte0_e32 v205, v11
	v_lshl_add_u64 v[206:207], v[6:7], 0, v[8:9]
	s_add_i32 s58, 0, 0x20210
	s_movk_i32 s59, 0x1900
	s_movk_i32 s80, 0x3200
	s_mov_b64 s[74:75], 0x1600
	s_movk_i32 s81, 0x1000
	s_mov_b32 s82, 0x6c00000
	s_mov_b32 s84, 0x6c01000
	v_mbcnt_hi_u32_b32 v185, -1, v2
	v_mov_b32_e32 v187, 0xff800000
	s_waitcnt lgkmcnt(0)
	s_barrier
	v_readfirstlane_b32 s98, v183
	s_bitcmp1_b32 s98, 8
	s_cbranch_scc0 .Lattprio3
	s_setprio 1

; __device__ __forceinline__ unsigned xb_ld(unsigned* p)              { return __hip_atomic_load(p, __ATOMIC_RELAXED, __HIP_MEMORY_SCOPE_AGENT); }
; __device__ __forceinline__ void xcd_barrier_complete(unsigned* bar, unsigned x, unsigned& nloc, unsigned& nx) {
;     const unsigned G = gridDim.x * gridDim.y * gridDim.z;
;     unsigned sum, cnt, mine, sp = 0u;
;     for (;;) {
;         sum = 0u; cnt = 0u; mine = 0u;
; #pragma unroll
;         for (unsigned j = 0; j < 16; ++j) { const unsigned c = xb_ld(&bar[XB_XCNT(j)]); sum += c; cnt += (c > 0u) ? 1u : 0u; mine = (j == x) ? c : mine; }
; __device__ __forceinline__ void xcd_barrier(const XcdBarrier& b) {
;     asm volatile("s_waitcnt vmcnt(0)" ::: "memory");
;     __syncthreads();
;     if (threadIdx.x == 0) {
;         unsigned* bar = b.bar;
;         __builtin_amdgcn_s_waitcnt(0);
;         unsigned nloc = b.st[0], nx = b.st[1];
;         if (nloc == 0u) { xcd_barrier_complete(bar, b.x, nloc, nx); b.st[0] = nloc; b.st[1] = nx; }
.LBB0_987:
	s_setprio 0
	s_cmp_gt_i32 s91, 4
	s_cselect_b64 s[4:5], -1, 0
	s_and_b64 s[6:7], s[52:53], s[4:5]
	s_andn2_b64 vcc, exec, s[6:7]
	s_cbranch_vccnz .LBB0_1055
	s_cmp_gt_i32 s90, -1
	s_mov_b64 s[6:7], -1
	s_cbranch_scc0 .LBB0_1042
	s_waitcnt vmcnt(0)
	s_waitcnt vmcnt(0)
	s_barrier
	s_mov_b64 s[6:7], exec
	v_readlane_b32 s8, v242, 0
	v_readlane_b32 s9, v242, 1
	s_and_b64 s[8:9], s[6:7], s[8:9]
	s_mov_b64 exec, s[8:9]
	s_cbranch_execz .LBB0_1041
	s_add_i32 s8, 0, 0x20200
	v_mov_b32_e32 v1, s8
	s_waitcnt vmcnt(0) expcnt(0) lgkmcnt(0)
	ds_read_b32 v3, v1
	s_add_i32 s8, 0, 0x20204
	v_mov_b32_e32 v1, s8
	ds_read_b32 v1, v1
	s_waitcnt lgkmcnt(1)
	v_cmp_ne_u32_e32 vcc, 0, v3
	s_cbranch_vccnz .LBB0_1005
	s_load_dword s8, s[0:1], 0xe8
	s_mov_b32 s47, 1
	v_mov_b32_e32 v17, 0
	s_waitcnt lgkmcnt(0)
	s_mul_i32 s33, s57, s8
	s_add_u32 s8, s48, 0x1bcc0200
	s_addc_u32 s9, s49, 0
	s_add_u32 s10, s48, 0x1bcc0400
	s_addc_u32 s11, s49, 0
	s_add_u32 s12, s48, 0x1bcc0500
	s_addc_u32 s13, s49, 0
	s_add_u32 s14, s48, 0x1bcc0600
	s_addc_u32 s15, s49, 0
	s_add_u32 s16, s48, 0x1bcc0700
	s_addc_u32 s17, s49, 0
	s_add_u32 s18, s48, 0x1bcc0800
	s_addc_u32 s19, s49, 0
	s_add_u32 s20, s48, 0x1bcc0900
	s_addc_u32 s21, s49, 0
	s_add_u32 s22, s48, 0x1bcc0a00
	s_addc_u32 s23, s49, 0
	s_add_u32 s24, s48, 0x1bcc0b00
	s_addc_u32 s25, s49, 0
	s_add_u32 s26, s48, 0x1bcc0c00
	s_addc_u32 s27, s49, 0
	s_add_u32 s28, s48, 0x1bcc0d00
	s_addc_u32 s29, s49, 0
	s_add_u32 s30, s48, 0x1bcc0e00
	s_addc_u32 s31, s49, 0
	s_add_u32 s34, s48, 0x1bcc0f00
	s_addc_u32 s35, s49, 0
	s_add_u32 s36, s48, 0x1bcc1000
	s_addc_u32 s37, s49, 0
	s_add_u32 s38, s48, 0x1bcc1100
	s_addc_u32 s39, s49, 0
	s_add_u32 s40, s48, 0x1bcc1200
	s_addc_u32 s41, s49, 0
	s_add_u32 s52, s48, 0x1bcc1300
	s_mul_i32 s33, s33, s56
	s_addc_u32 s53, s49, 0
	s_branch .LBB0_993

; DI int crow(int reg, int h) { return (reg & 3) + 8 * (reg >> 2) + 4 * h; }
;     DI void init_s(f32x16& s, int) const { zero16(s); }
;     DI void init_s(f32x16& s, int) const { zero16(s); }
;     DI void init_s(f32x16& s, int) const { zero16(s); }
;     DI void init_s(f32x16& s, int tl) const { const int h = (threadIdx.x & 63) >> 5; const float c0 = slope2 * (float)(32 * tl) - lc;
; #pragma unroll
;         for (int i = 0; i < 16; ++i) s[i] = slope2 * (float)crow(i, h) + c0; }
;     DI void post_s(f32x16& s, int tl, int r, int h) const {
;         if (tl == g - 4) {
; #pragma unroll
;             for (int i = 0; i < 16; ++i) s[i] = crow(i, h) > r ? s[i] : -INFINITY; }
;         if (tl == g) {
; #pragma unroll
;             for (int i = 0; i < 16; ++i) s[i] = crow(i, h) <= r ? s[i] : -INFINITY; } }
.LBB0_1064:
	s_waitcnt vmcnt(0) lgkmcnt(0)
	s_barrier
	s_mov_b64 s[4:5], exec
	v_readlane_b32 s6, v242, 0
	v_readlane_b32 s7, v242, 1
	s_and_b64 s[6:7], s[4:5], s[6:7]
	s_mov_b64 exec, s[6:7]
	s_add_i32 s6, 0, 0x20210
	v_mov_b32_e32 v2, 0
	v_mov_b32_e32 v3, s6
	ds_write_b32 v3, v2
	s_or_b64 exec, exec, s[4:5]
	v_and_b32_e32 v6, 1, v176
	v_and_b32_e32 v185, 31, v183
	v_lshlrev_b32_e32 v2, 9, v6
	v_mov_b32_e32 v3, 0
	v_lshl_add_u64 v[4:5], s[68:69], 0, v[2:3]
	v_lshlrev_b32_e32 v8, 4, v185
	v_mov_b32_e32 v9, v3
	v_lshlrev_b32_e32 v186, 2, v6
	v_lshl_add_u64 v[188:189], v[4:5], 0, v[8:9]
	v_cvt_f32_ubyte0_e32 v4, s33
	v_lshlrev_b32_e32 v184, 3, v6
	v_or_b32_e32 v6, 2, v186
	v_rcp_iflag_f32_e32 v4, v4
	v_cmp_gt_u32_e64 s[10:11], v6, v185
	v_or_b32_e32 v6, 3, v186
	v_cmp_gt_u32_e64 s[12:13], v6, v185
	v_or_b32_e32 v6, 8, v186
	v_and_b32_e32 v1, 4, v1
	v_cmp_gt_u32_e64 s[14:15], v6, v185
	v_or_b32_e32 v6, 9, v186
	v_or_b32_e32 v10, 1, v1
	v_or_b32_e32 v11, 3, v1
	v_or_b32_e32 v12, 2, v1
	v_or_b32_e32 v13, 9, v1
	v_or_b32_e32 v14, 8, v1
	v_or_b32_e32 v15, 11, v1
	v_or_b32_e32 v16, 10, v1
	v_or_b32_e32 v17, 17, v1
	v_or_b32_e32 v18, 16, v1
	v_or_b32_e32 v19, 19, v1
	v_or_b32_e32 v20, 18, v1
	v_or_b32_e32 v21, 25, v1
	v_or_b32_e32 v22, 24, v1
	v_or_b32_e32 v23, 27, v1
	v_or_b32_e32 v24, 26, v1
	v_cmp_gt_u32_e64 s[16:17], v6, v185
	v_or_b32_e32 v6, 10, v186
	v_cvt_f32_ubyte0_e32 v204, v1
	v_mul_f32_e32 v1, 0x4f7ffffe, v4
	v_cmp_gt_u32_e64 s[18:19], v6, v185
	v_or_b32_e32 v6, 11, v186
	v_cvt_u32_f32_e32 v1, v1
	v_cmp_gt_u32_e64 s[20:21], v6, v185
	v_or_b32_e32 v6, 16, v186
	v_cmp_gt_u32_e64 s[22:23], v6, v185
	v_or_b32_e32 v6, 17, v186
	v_cmp_gt_u32_e64 s[24:25], v6, v185
	v_or_b32_e32 v6, 18, v186
	v_cmp_gt_u32_e64 s[26:27], v6, v185
	v_or_b32_e32 v6, 19, v186
	s_sub_i32 s40, 0, s33
	v_readfirstlane_b32 s41, v1
	v_cmp_gt_u32_e64 s[28:29], v6, v185
	v_or_b32_e32 v6, 24, v186
	s_mul_i32 s40, s40, s41
	v_cmp_gt_u32_e64 s[30:31], v6, v185
	v_or_b32_e32 v6, 25, v186
	s_mul_hi_u32 s40, s41, s40
	v_cmp_gt_u32_e64 s[34:35], v6, v185
	v_or_b32_e32 v6, 26, v186
	s_add_i32 s51, s41, s40
	v_lshlrev_b32_e32 v1, 5, v183
	s_movk_i32 s40, 0x400
	v_cmp_gt_u32_e64 s[36:37], v6, v185
	v_or_b32_e32 v6, 27, v186
	v_and_or_b32 v4, v1, s40, v8
	v_mov_b32_e32 v5, v3
	v_cmp_gt_u32_e64 s[38:39], v6, v185
	v_lshl_add_u64 v[6:7], s[66:67], 0, v[2:3]
	v_lshl_add_u64 v[4:5], s[42:43], 0, v[4:5]
	s_mov_b64 s[40:41], 0x6e00800
	v_or_b32_e32 v2, v2, v8
	v_lshl_add_u64 v[208:209], v[4:5], 0, s[40:41]
	v_lshl_add_u64 v[210:211], s[42:43], 0, v[2:3]
	s_mov_b64 s[40:41], 0x7602800
	v_lshl_add_u64 v[212:213], v[210:211], 0, s[40:41]
	v_lshlrev_b32_e32 v1, 6, v183
	s_movk_i32 s40, 0x800
	v_and_or_b32 v2, v1, s40, v8
	v_mbcnt_lo_u32_b32 v1, -1, 0
	s_mov_b32 s75, 0
	v_cmp_eq_u32_e64 s[4:5], 0, v182
	s_add_i32 s47, s2, -16
	s_add_i32 s50, s2, 0xf00
	v_cmp_gt_u32_e64 s[6:7], v186, v185
	v_cmp_lt_u32_e64 s[8:9], v186, v185
	v_cvt_f32_ubyte0_e32 v191, v23
	v_cvt_f32_ubyte0_e32 v190, v24
	v_cvt_f32_ubyte0_e32 v193, v21
	v_cvt_f32_ubyte0_e32 v192, v22
	v_cvt_f32_ubyte0_e32 v195, v19
	v_cvt_f32_ubyte0_e32 v194, v20
	v_cvt_f32_ubyte0_e32 v197, v17
	v_cvt_f32_ubyte0_e32 v196, v18
	v_cvt_f32_ubyte0_e32 v199, v15
	v_cvt_f32_ubyte0_e32 v198, v16
	v_cvt_f32_ubyte0_e32 v201, v13
	v_cvt_f32_ubyte0_e32 v200, v14
	v_cvt_f32_ubyte0_e32 v203, v11
	v_cvt_f32_ubyte0_e32 v202, v12
	v_cvt_f32_ubyte0_e32 v205, v10
	v_lshl_add_u64 v[206:207], v[6:7], 0, v[8:9]
	v_lshl_add_u64 v[214:215], s[42:43], 0, v[2:3]
	s_add_i32 s58, 0, 0x20210
	s_movk_i32 s59, 0x1900
	s_movk_i32 s78, 0x3200
	s_mov_b64 s[66:67], 0x1600
	s_movk_i32 s79, 0x1000
	s_mov_b32 s80, 0x6c00000
	s_mov_b32 s81, 0x6c01000
	v_mbcnt_hi_u32_b32 v1, -1, v1
	v_mov_b32_e32 v187, 0xff800000
	s_waitcnt lgkmcnt(0)
	s_barrier
	v_readfirstlane_b32 s98, v183
	s_bitcmp1_b32 s98, 8
	s_cbranch_scc0 .Lattprio4
	s_setprio 1

; #define SEAM(k) do { if (IN(k) && IN((k) + 1)) { if (P.ph_lo < 0) grid.sync(); else xcd_barrier(xbar); } } while (0)
; __global__ void __launch_bounds__(512, 2) fwd_kernel(Params P) {
;     ...
;         ATT_RUN(ATT_SPLIT, ATT_TOTAL, 2);
;     }
;     SEAM(4);
.LBB0_1097:
	s_setprio 0
	s_cmp_gt_i32 s91, 5
	s_cselect_b64 s[4:5], -1, 0
	s_and_b64 s[6:7], s[52:53], s[4:5]
	s_branch .LBB0_1165
